# barrier trims + split-K fix-up pieces touched with 16 loads in flight before the serialised reduction
# baseline (speedup 1.0000x reference)
.LBB0_388:
	v_add_u32_e32 v2, s97, v194
	v_readlane_b32 s2, v255, 1
	v_ashrrev_i32_e32 v3, 31, v2
	v_readlane_b32 s3, v255, 2
	s_and_b64 vcc, exec, s[70:71]
	s_waitcnt vmcnt(0) lgkmcnt(0)
	v_lshl_add_u64 v[124:125], v[2:3], 4, s[2:3]
	s_barrier
	v_readlane_b32 s100, v255, 33
	s_nop 3
	s_and_b32 s100, s100, 3
	s_lshl_b32 s100, s100, 11
	s_mov_b32 s101, 0
	v_lshl_add_u64 v[242:243], s[100:101], 0, v[124:125]
	global_load_dwordx4 v[244:247], v[242:243], off
	global_load_dwordx4 v[248:251], v[242:243], off offset:1024
	s_mov_b32 s100, 0x20000
	v_lshl_add_u64 v[252:253], s[100:101], 0, v[242:243]
	global_load_dwordx4 v[244:247], v[252:253], off
	global_load_dwordx4 v[248:251], v[252:253], off offset:1024
	s_mov_b32 s100, 0x40000
	v_lshl_add_u64 v[252:253], s[100:101], 0, v[242:243]
	global_load_dwordx4 v[244:247], v[252:253], off
	global_load_dwordx4 v[248:251], v[252:253], off offset:1024
	s_mov_b32 s100, 0x60000
	v_lshl_add_u64 v[252:253], s[100:101], 0, v[242:243]
	global_load_dwordx4 v[244:247], v[252:253], off
	global_load_dwordx4 v[248:251], v[252:253], off offset:1024
	s_mov_b32 s100, 0x2000
	v_lshl_add_u64 v[252:253], s[100:101], 0, v[242:243]
	global_load_dwordx4 v[244:247], v[252:253], off
	global_load_dwordx4 v[248:251], v[252:253], off offset:1024
	s_mov_b32 s100, 0x22000
	v_lshl_add_u64 v[252:253], s[100:101], 0, v[242:243]
	global_load_dwordx4 v[244:247], v[252:253], off
	global_load_dwordx4 v[248:251], v[252:253], off offset:1024
	s_mov_b32 s100, 0x42000
	v_lshl_add_u64 v[252:253], s[100:101], 0, v[242:243]
	global_load_dwordx4 v[244:247], v[252:253], off
	global_load_dwordx4 v[248:251], v[252:253], off offset:1024
	s_mov_b32 s100, 0x62000
	v_lshl_add_u64 v[252:253], s[100:101], 0, v[242:243]
	global_load_dwordx4 v[244:247], v[252:253], off
	global_load_dwordx4 v[248:251], v[252:253], off offset:1024
	s_waitcnt vmcnt(0)
	s_cbranch_vccnz .LBB0_392
	v_mov_b32_e32 v2, v0
	v_mov_b32_e32 v3, v0
	v_mov_b32_e32 v1, v0
	v_mov_b64_e32 v[6:7], v[2:3]
	v_mov_b64_e32 v[10:11], v[2:3]
	v_mov_b64_e32 v[4:5], v[0:1]
	v_mov_b64_e32 v[8:9], v[0:1]
	v_cndmask_b32_e64 v1, 0, 1, s[70:71]
	v_cmp_ne_u32_e64 s[2:3], 1, v1
	s_andn2_b64 vcc, exec, s[70:71]
	s_cbranch_vccz .LBB0_393

.LBB0_2066:
	s_and_b32 s2, s9, -8
	s_sub_i32 s22, s91, s2
	s_lshl_b32 s2, s8, 3
	s_ashr_i32 s3, s2, 31
	s_lshl_b64 s[2:3], s[2:3], 17
	v_readlane_b32 s4, v254, 63
	v_readlane_b32 s5, v255, 0
	s_add_u32 s2, s4, s2
	s_addc_u32 s3, s5, s3
	v_add_u32_e32 v0, s97, v239
	v_ashrrev_i32_e32 v1, 31, v0
	s_cmp_eq_u32 s22, 0
	v_lshl_add_u64 v[0:1], v[0:1], 4, s[2:3]
	s_cselect_b64 s[2:3], -1, 0
	v_mov_b32_e32 v68, 0
	s_and_b64 vcc, exec, s[2:3]
	v_mov_b32_e32 v64, 0
	v_mov_b32_e32 v65, 0
	v_mov_b32_e32 v66, 0
	v_mov_b32_e32 v67, 0
	v_mov_b32_e32 v70, 0
	v_mov_b32_e32 v71, 0
	v_mov_b32_e32 v72, 0
	v_mov_b32_e32 v73, 0
	s_waitcnt vmcnt(0)
	s_barrier
	v_readlane_b32 s100, v255, 33
	s_nop 3
	s_and_b32 s100, s100, 7
	s_lshl_b32 s100, s100, 11
	s_mov_b32 s101, 0
	v_lshl_add_u64 v[242:243], s[100:101], 0, v[0:1]
	global_load_dwordx4 v[244:247], v[242:243], off
	global_load_dwordx4 v[248:251], v[242:243], off offset:1024
	s_mov_b32 s100, 0x20000
	v_lshl_add_u64 v[252:253], s[100:101], 0, v[242:243]
	global_load_dwordx4 v[244:247], v[252:253], off
	global_load_dwordx4 v[248:251], v[252:253], off offset:1024
	s_mov_b32 s100, 0x40000
	v_lshl_add_u64 v[252:253], s[100:101], 0, v[242:243]
	global_load_dwordx4 v[244:247], v[252:253], off
	global_load_dwordx4 v[248:251], v[252:253], off offset:1024
	s_mov_b32 s100, 0x60000
	v_lshl_add_u64 v[252:253], s[100:101], 0, v[242:243]
	global_load_dwordx4 v[244:247], v[252:253], off
	global_load_dwordx4 v[248:251], v[252:253], off offset:1024
	s_mov_b32 s100, 0x80000
	v_lshl_add_u64 v[252:253], s[100:101], 0, v[242:243]
	global_load_dwordx4 v[244:247], v[252:253], off
	global_load_dwordx4 v[248:251], v[252:253], off offset:1024
	s_mov_b32 s100, 0xa0000
	v_lshl_add_u64 v[252:253], s[100:101], 0, v[242:243]
	global_load_dwordx4 v[244:247], v[252:253], off
	global_load_dwordx4 v[248:251], v[252:253], off offset:1024
	s_mov_b32 s100, 0xc0000
	v_lshl_add_u64 v[252:253], s[100:101], 0, v[242:243]
	global_load_dwordx4 v[244:247], v[252:253], off
	global_load_dwordx4 v[248:251], v[252:253], off offset:1024
	s_mov_b32 s100, 0xe0000
	v_lshl_add_u64 v[252:253], s[100:101], 0, v[242:243]
	global_load_dwordx4 v[244:247], v[252:253], off
	global_load_dwordx4 v[248:251], v[252:253], off offset:1024
	s_waitcnt vmcnt(0)
	s_cbranch_vccz .LBB0_2068
	s_mov_b32 s4, 0x20000
	v_add_co_u32_e32 v6, vcc, s4, v0
	s_mov_b32 s4, 0x40000
	s_nop 0
	v_addc_co_u32_e32 v7, vcc, 0, v1, vcc
	v_add_co_u32_e32 v10, vcc, s4, v0
	s_mov_b32 s4, 0x60000
	s_nop 0
	v_addc_co_u32_e32 v11, vcc, 0, v1, vcc
	global_load_dwordx4 v[2:5], v[0:1], off
	v_add_co_u32_e32 v14, vcc, s4, v0
	global_load_dwordx4 v[6:9], v[6:7], off
	s_nop 0
	v_addc_co_u32_e32 v15, vcc, 0, v1, vcc
	s_mov_b32 s4, 0x80000
	global_load_dwordx4 v[10:13], v[10:11], off
	v_add_co_u32_e32 v18, vcc, s4, v0
	global_load_dwordx4 v[14:17], v[14:15], off
	s_nop 0
	v_addc_co_u32_e32 v19, vcc, 0, v1, vcc
	s_mov_b32 s4, 0xa0000
	global_load_dwordx4 v[18:21], v[18:19], off
	v_add_co_u32_e32 v22, vcc, s4, v0
	s_mov_b32 s4, 0xc0000
	s_nop 0
	v_addc_co_u32_e32 v23, vcc, 0, v1, vcc
	global_load_dwordx4 v[22:25], v[22:23], off
	v_add_co_u32_e32 v26, vcc, s4, v0
	s_mov_b32 s4, 0xe0000
	s_nop 0
	v_addc_co_u32_e32 v27, vcc, 0, v1, vcc
	global_load_dwordx4 v[26:29], v[26:27], off
	v_add_co_u32_e32 v30, vcc, s4, v0
	s_waitcnt vmcnt(6)
	v_lshlrev_b32_e32 v34, 16, v2
	v_addc_co_u32_e32 v31, vcc, 0, v1, vcc
	global_load_dwordx4 v[30:33], v[30:31], off
	v_and_b32_e32 v35, 0xffff0000, v2
	v_lshlrev_b32_e32 v2, 16, v3
	v_and_b32_e32 v3, 0xffff0000, v3
	v_lshlrev_b32_e32 v36, 16, v4
	v_and_b32_e32 v37, 0xffff0000, v4
	v_lshlrev_b32_e32 v4, 16, v5
	v_and_b32_e32 v5, 0xffff0000, v5
	v_pk_add_f32 v[34:35], v[34:35], 0 op_sel_hi:[1,0]
	v_pk_add_f32 v[2:3], v[2:3], 0 op_sel_hi:[1,0]
	v_pk_add_f32 v[4:5], v[4:5], 0 op_sel_hi:[1,0]
	s_waitcnt vmcnt(6)
	v_lshlrev_b32_e32 v38, 16, v6
	v_and_b32_e32 v39, 0xffff0000, v6
	v_lshlrev_b32_e32 v6, 16, v7
	v_and_b32_e32 v7, 0xffff0000, v7
	v_lshlrev_b32_e32 v40, 16, v8
	v_and_b32_e32 v41, 0xffff0000, v8
	v_lshlrev_b32_e32 v8, 16, v9
	v_and_b32_e32 v9, 0xffff0000, v9
	v_pk_add_f32 v[36:37], v[36:37], 0 op_sel_hi:[1,0]
	s_waitcnt vmcnt(5)
	v_lshlrev_b32_e32 v42, 16, v10
	v_and_b32_e32 v43, 0xffff0000, v10
	v_lshlrev_b32_e32 v10, 16, v11
	v_and_b32_e32 v11, 0xffff0000, v11
	v_lshlrev_b32_e32 v44, 16, v12
	v_and_b32_e32 v45, 0xffff0000, v12
	v_lshlrev_b32_e32 v12, 16, v13
	v_and_b32_e32 v13, 0xffff0000, v13
	v_pk_add_f32 v[2:3], v[2:3], v[6:7]
	v_pk_add_f32 v[6:7], v[34:35], v[38:39]
	v_pk_add_f32 v[4:5], v[4:5], v[8:9]
	s_waitcnt vmcnt(4)
	v_lshlrev_b32_e32 v46, 16, v14
	v_and_b32_e32 v47, 0xffff0000, v14
	v_lshlrev_b32_e32 v14, 16, v15
	v_and_b32_e32 v15, 0xffff0000, v15
	v_pk_add_f32 v[8:9], v[36:37], v[40:41]
	v_pk_add_f32 v[6:7], v[6:7], v[42:43]
	v_pk_add_f32 v[2:3], v[2:3], v[10:11]
	v_pk_add_f32 v[4:5], v[4:5], v[12:13]
	v_lshlrev_b32_e32 v10, 16, v17
	v_and_b32_e32 v11, 0xffff0000, v17
	v_lshlrev_b32_e32 v48, 16, v16
	v_pk_add_f32 v[8:9], v[8:9], v[44:45]
	v_pk_add_f32 v[2:3], v[2:3], v[14:15]
	v_pk_add_f32 v[6:7], v[6:7], v[46:47]
	v_and_b32_e32 v49, 0xffff0000, v16
	v_pk_add_f32 v[4:5], v[4:5], v[10:11]
	s_waitcnt vmcnt(3)
	v_lshlrev_b32_e32 v10, 16, v18
	v_and_b32_e32 v11, 0xffff0000, v18
	v_lshlrev_b32_e32 v12, 16, v19
	v_and_b32_e32 v13, 0xffff0000, v19
	v_pk_add_f32 v[8:9], v[8:9], v[48:49]
	v_pk_add_f32 v[6:7], v[6:7], v[10:11]
	v_pk_add_f32 v[2:3], v[2:3], v[12:13]
	v_lshlrev_b32_e32 v10, 16, v20
	v_and_b32_e32 v11, 0xffff0000, v20
	v_lshlrev_b32_e32 v12, 16, v21
	v_and_b32_e32 v13, 0xffff0000, v21
	v_pk_add_f32 v[8:9], v[8:9], v[10:11]
	v_pk_add_f32 v[4:5], v[4:5], v[12:13]
	s_waitcnt vmcnt(2)
	v_lshlrev_b32_e32 v10, 16, v22
	v_and_b32_e32 v11, 0xffff0000, v22
	v_lshlrev_b32_e32 v12, 16, v23
	v_and_b32_e32 v13, 0xffff0000, v23
	v_pk_add_f32 v[2:3], v[2:3], v[12:13]
	v_pk_add_f32 v[6:7], v[6:7], v[10:11]
	v_lshlrev_b32_e32 v10, 16, v24
	v_and_b32_e32 v11, 0xffff0000, v24
	v_lshlrev_b32_e32 v12, 16, v25
	v_and_b32_e32 v13, 0xffff0000, v25
	v_pk_add_f32 v[4:5], v[4:5], v[12:13]
	v_pk_add_f32 v[8:9], v[8:9], v[10:11]
	s_waitcnt vmcnt(1)
	v_lshlrev_b32_e32 v10, 16, v26
	v_and_b32_e32 v11, 0xffff0000, v26
	v_lshlrev_b32_e32 v12, 16, v27
	v_and_b32_e32 v13, 0xffff0000, v27
	v_pk_add_f32 v[6:7], v[6:7], v[10:11]
	v_pk_add_f32 v[2:3], v[2:3], v[12:13]
	v_lshlrev_b32_e32 v10, 16, v28
	v_and_b32_e32 v11, 0xffff0000, v28
	v_lshlrev_b32_e32 v12, 16, v29
	v_and_b32_e32 v13, 0xffff0000, v29
	v_pk_add_f32 v[8:9], v[8:9], v[10:11]
	v_pk_add_f32 v[4:5], v[4:5], v[12:13]
	s_waitcnt vmcnt(0)
	v_lshlrev_b32_e32 v10, 16, v30
	v_and_b32_e32 v11, 0xffff0000, v30
	v_lshlrev_b32_e32 v12, 16, v31
	v_and_b32_e32 v13, 0xffff0000, v31
	v_pk_add_f32 v[66:67], v[2:3], v[12:13]
	v_pk_add_f32 v[64:65], v[6:7], v[10:11]
	v_lshlrev_b32_e32 v2, 16, v32
	v_and_b32_e32 v3, 0xffff0000, v32
	v_lshlrev_b32_e32 v6, 16, v33
	v_and_b32_e32 v7, 0xffff0000, v33
	v_pk_add_f32 v[72:73], v[4:5], v[6:7]
	v_pk_add_f32 v[70:71], v[8:9], v[2:3]

.LBB0_2319:
	s_lshl_b32 s4, s10, 1
	s_ashr_i32 s5, s4, 31
	s_sub_i32 s18, s91, s4
	s_lshl_b64 s[4:5], s[4:5], 17
	v_readlane_b32 s8, v254, 63
	v_readlane_b32 s9, v255, 0
	s_add_u32 s4, s8, s4
	s_addc_u32 s5, s9, s5
	v_add_u32_e32 v0, s97, v128
	v_ashrrev_i32_e32 v1, 31, v0
	s_cmp_eq_u32 s18, 0
	v_lshl_add_u64 v[12:13], v[0:1], 4, s[4:5]
	s_cselect_b64 s[4:5], -1, 0
	v_mov_b32_e32 v0, 0
	s_and_b64 vcc, exec, s[4:5]
	v_mov_b32_e32 v2, 0
	v_mov_b32_e32 v3, 0
	v_mov_b32_e32 v6, 0
	v_mov_b32_e32 v7, 0
	v_mov_b32_e32 v4, 0
	v_mov_b32_e32 v5, 0
	v_mov_b32_e32 v8, 0
	v_mov_b32_e32 v9, 0
	s_waitcnt vmcnt(0)
	s_barrier
	v_readlane_b32 s100, v255, 33
	s_nop 3
	s_and_b32 s100, s100, 1
	s_lshl_b32 s100, s100, 11
	s_mov_b32 s101, 0
	v_lshl_add_u64 v[242:243], s[100:101], 0, v[12:13]
	global_load_dwordx4 v[244:247], v[242:243], off
	global_load_dwordx4 v[248:251], v[242:243], off offset:1024
	s_mov_b32 s100, 0x20000
	v_lshl_add_u64 v[252:253], s[100:101], 0, v[242:243]
	global_load_dwordx4 v[244:247], v[252:253], off
	global_load_dwordx4 v[248:251], v[252:253], off offset:1024
	s_mov_b32 s100, 0x1000
	v_lshl_add_u64 v[252:253], s[100:101], 0, v[242:243]
	global_load_dwordx4 v[244:247], v[252:253], off
	global_load_dwordx4 v[248:251], v[252:253], off offset:1024
	s_mov_b32 s100, 0x21000
	v_lshl_add_u64 v[252:253], s[100:101], 0, v[242:243]
	global_load_dwordx4 v[244:247], v[252:253], off
	global_load_dwordx4 v[248:251], v[252:253], off offset:1024
	s_mov_b32 s100, 0x2000
	v_lshl_add_u64 v[252:253], s[100:101], 0, v[242:243]
	global_load_dwordx4 v[244:247], v[252:253], off
	global_load_dwordx4 v[248:251], v[252:253], off offset:1024
	s_mov_b32 s100, 0x22000
	v_lshl_add_u64 v[252:253], s[100:101], 0, v[242:243]
	global_load_dwordx4 v[244:247], v[252:253], off
	global_load_dwordx4 v[248:251], v[252:253], off offset:1024
	s_mov_b32 s100, 0x3000
	v_lshl_add_u64 v[252:253], s[100:101], 0, v[242:243]
	global_load_dwordx4 v[244:247], v[252:253], off
	global_load_dwordx4 v[248:251], v[252:253], off offset:1024
	s_mov_b32 s100, 0x23000
	v_lshl_add_u64 v[252:253], s[100:101], 0, v[242:243]
	global_load_dwordx4 v[244:247], v[252:253], off
	global_load_dwordx4 v[248:251], v[252:253], off offset:1024
	s_waitcnt vmcnt(0)
	s_cbranch_vccz .LBB0_2321
	s_mov_b32 s8, 0x20000
	v_add_co_u32_e32 v6, vcc, s8, v12
	global_load_dwordx4 v[2:5], v[12:13], off
	s_nop 0
	v_addc_co_u32_e32 v7, vcc, 0, v13, vcc
	global_load_dwordx4 v[6:9], v[6:7], off
	s_waitcnt vmcnt(1)
	v_lshlrev_b32_e32 v10, 16, v2
	v_and_b32_e32 v11, 0xffff0000, v2
	v_lshlrev_b32_e32 v2, 16, v3
	v_and_b32_e32 v3, 0xffff0000, v3
	v_lshlrev_b32_e32 v14, 16, v4
	v_and_b32_e32 v15, 0xffff0000, v4
	v_lshlrev_b32_e32 v4, 16, v5
	v_and_b32_e32 v5, 0xffff0000, v5
	v_pk_add_f32 v[10:11], v[10:11], 0 op_sel_hi:[1,0]
	v_pk_add_f32 v[2:3], v[2:3], 0 op_sel_hi:[1,0]
	v_pk_add_f32 v[14:15], v[14:15], 0 op_sel_hi:[1,0]
	v_pk_add_f32 v[4:5], v[4:5], 0 op_sel_hi:[1,0]
	s_waitcnt vmcnt(0)
	v_lshlrev_b32_e32 v16, 16, v6
	v_and_b32_e32 v17, 0xffff0000, v6
	v_lshlrev_b32_e32 v6, 16, v7
	v_and_b32_e32 v7, 0xffff0000, v7
	v_lshlrev_b32_e32 v18, 16, v8
	v_and_b32_e32 v19, 0xffff0000, v8
	v_lshlrev_b32_e32 v8, 16, v9
	v_and_b32_e32 v9, 0xffff0000, v9
	v_pk_add_f32 v[6:7], v[2:3], v[6:7]
	v_pk_add_f32 v[2:3], v[10:11], v[16:17]
	v_pk_add_f32 v[8:9], v[4:5], v[8:9]
	v_pk_add_f32 v[4:5], v[14:15], v[18:19]

.LBB0_2483:
	s_lshl_b32 s0, s4, 3
	s_ashr_i32 s1, s0, 31
	s_sub_i32 s22, s91, s0
	s_lshl_b64 s[0:1], s[0:1], 17
	v_readlane_b32 s2, v254, 63
	v_readlane_b32 s3, v255, 0
	s_add_u32 s0, s2, s0
	s_addc_u32 s1, s3, s1
	v_add_u32_e32 v0, s97, v224
	s_cmp_eq_u32 s22, 0
	v_ashrrev_i32_e32 v1, 31, v0
	s_cselect_b64 s[16:17], -1, 0
	v_lshl_add_u64 v[0:1], v[0:1], 4, s[0:1]
	v_mov_b32_e32 v64, 0
	s_and_b64 vcc, exec, s[16:17]
	v_mov_b32_e32 v70, 0
	v_mov_b32_e32 v71, 0
	v_mov_b32_e32 v72, 0
	v_mov_b32_e32 v73, 0
	v_mov_b32_e32 v66, 0
	v_mov_b32_e32 v67, 0
	v_mov_b32_e32 v68, 0
	v_mov_b32_e32 v69, 0
	s_waitcnt vmcnt(0)
	s_barrier
	v_readlane_b32 s100, v255, 33
	s_nop 3
	s_and_b32 s100, s100, 7
	s_lshl_b32 s100, s100, 11
	s_mov_b32 s101, 0
	v_lshl_add_u64 v[242:243], s[100:101], 0, v[0:1]
	global_load_dwordx4 v[244:247], v[242:243], off
	global_load_dwordx4 v[248:251], v[242:243], off offset:1024
	s_mov_b32 s100, 0x20000
	v_lshl_add_u64 v[252:253], s[100:101], 0, v[242:243]
	global_load_dwordx4 v[244:247], v[252:253], off
	global_load_dwordx4 v[248:251], v[252:253], off offset:1024
	s_mov_b32 s100, 0x40000
	v_lshl_add_u64 v[252:253], s[100:101], 0, v[242:243]
	global_load_dwordx4 v[244:247], v[252:253], off
	global_load_dwordx4 v[248:251], v[252:253], off offset:1024
	s_mov_b32 s100, 0x60000
	v_lshl_add_u64 v[252:253], s[100:101], 0, v[242:243]
	global_load_dwordx4 v[244:247], v[252:253], off
	global_load_dwordx4 v[248:251], v[252:253], off offset:1024
	s_mov_b32 s100, 0x80000
	v_lshl_add_u64 v[252:253], s[100:101], 0, v[242:243]
	global_load_dwordx4 v[244:247], v[252:253], off
	global_load_dwordx4 v[248:251], v[252:253], off offset:1024
	s_mov_b32 s100, 0xa0000
	v_lshl_add_u64 v[252:253], s[100:101], 0, v[242:243]
	global_load_dwordx4 v[244:247], v[252:253], off
	global_load_dwordx4 v[248:251], v[252:253], off offset:1024
	s_mov_b32 s100, 0xc0000
	v_lshl_add_u64 v[252:253], s[100:101], 0, v[242:243]
	global_load_dwordx4 v[244:247], v[252:253], off
	global_load_dwordx4 v[248:251], v[252:253], off offset:1024
	s_mov_b32 s100, 0xe0000
	v_lshl_add_u64 v[252:253], s[100:101], 0, v[242:243]
	global_load_dwordx4 v[244:247], v[252:253], off
	global_load_dwordx4 v[248:251], v[252:253], off offset:1024
	s_waitcnt vmcnt(0)
	s_cbranch_vccz .LBB0_2485
	s_mov_b32 s0, 0x20000
	v_add_co_u32_e32 v6, vcc, s0, v0
	s_mov_b32 s0, 0x40000
	s_nop 0
	v_addc_co_u32_e32 v7, vcc, 0, v1, vcc
	v_add_co_u32_e32 v10, vcc, s0, v0
	s_mov_b32 s0, 0x60000
	s_nop 0
	v_addc_co_u32_e32 v11, vcc, 0, v1, vcc
	global_load_dwordx4 v[2:5], v[0:1], off
	v_add_co_u32_e32 v14, vcc, s0, v0
	global_load_dwordx4 v[6:9], v[6:7], off
	s_nop 0
	v_addc_co_u32_e32 v15, vcc, 0, v1, vcc
	s_mov_b32 s0, 0x80000
	global_load_dwordx4 v[10:13], v[10:11], off
	v_add_co_u32_e32 v18, vcc, s0, v0
	global_load_dwordx4 v[14:17], v[14:15], off
	s_nop 0
	v_addc_co_u32_e32 v19, vcc, 0, v1, vcc
	s_mov_b32 s0, 0xa0000
	global_load_dwordx4 v[18:21], v[18:19], off
	v_add_co_u32_e32 v22, vcc, s0, v0
	s_mov_b32 s0, 0xc0000
	s_nop 0
	v_addc_co_u32_e32 v23, vcc, 0, v1, vcc
	global_load_dwordx4 v[22:25], v[22:23], off
	v_add_co_u32_e32 v26, vcc, s0, v0
	s_mov_b32 s0, 0xe0000
	s_nop 0
	v_addc_co_u32_e32 v27, vcc, 0, v1, vcc
	global_load_dwordx4 v[26:29], v[26:27], off
	v_add_co_u32_e32 v30, vcc, s0, v0
	s_waitcnt vmcnt(6)
	v_lshlrev_b32_e32 v34, 16, v2
	v_addc_co_u32_e32 v31, vcc, 0, v1, vcc
	global_load_dwordx4 v[30:33], v[30:31], off
	v_and_b32_e32 v35, 0xffff0000, v2
	v_lshlrev_b32_e32 v2, 16, v3
	v_and_b32_e32 v3, 0xffff0000, v3
	v_lshlrev_b32_e32 v36, 16, v4
	v_and_b32_e32 v37, 0xffff0000, v4
	v_lshlrev_b32_e32 v4, 16, v5
	v_and_b32_e32 v5, 0xffff0000, v5
	v_pk_add_f32 v[34:35], v[34:35], 0 op_sel_hi:[1,0]
	v_pk_add_f32 v[2:3], v[2:3], 0 op_sel_hi:[1,0]
	v_pk_add_f32 v[4:5], v[4:5], 0 op_sel_hi:[1,0]
	s_waitcnt vmcnt(6)
	v_lshlrev_b32_e32 v38, 16, v6
	v_and_b32_e32 v39, 0xffff0000, v6
	v_lshlrev_b32_e32 v6, 16, v7
	v_and_b32_e32 v7, 0xffff0000, v7
	v_lshlrev_b32_e32 v40, 16, v8
	v_and_b32_e32 v41, 0xffff0000, v8
	v_lshlrev_b32_e32 v8, 16, v9
	v_and_b32_e32 v9, 0xffff0000, v9
	v_pk_add_f32 v[36:37], v[36:37], 0 op_sel_hi:[1,0]
	s_waitcnt vmcnt(5)
	v_lshlrev_b32_e32 v42, 16, v10
	v_and_b32_e32 v43, 0xffff0000, v10
	v_lshlrev_b32_e32 v10, 16, v11
	v_and_b32_e32 v11, 0xffff0000, v11
	v_lshlrev_b32_e32 v44, 16, v12
	v_and_b32_e32 v45, 0xffff0000, v12
	v_lshlrev_b32_e32 v12, 16, v13
	v_and_b32_e32 v13, 0xffff0000, v13
	v_pk_add_f32 v[2:3], v[2:3], v[6:7]
	v_pk_add_f32 v[6:7], v[34:35], v[38:39]
	v_pk_add_f32 v[4:5], v[4:5], v[8:9]
	s_waitcnt vmcnt(4)
	v_lshlrev_b32_e32 v46, 16, v14
	v_and_b32_e32 v47, 0xffff0000, v14
	v_lshlrev_b32_e32 v14, 16, v15
	v_and_b32_e32 v15, 0xffff0000, v15
	v_pk_add_f32 v[8:9], v[36:37], v[40:41]
	v_pk_add_f32 v[6:7], v[6:7], v[42:43]
	v_pk_add_f32 v[2:3], v[2:3], v[10:11]
	v_pk_add_f32 v[4:5], v[4:5], v[12:13]
	v_lshlrev_b32_e32 v10, 16, v17
	v_and_b32_e32 v11, 0xffff0000, v17
	v_lshlrev_b32_e32 v48, 16, v16
	v_pk_add_f32 v[8:9], v[8:9], v[44:45]
	v_pk_add_f32 v[2:3], v[2:3], v[14:15]
	v_pk_add_f32 v[6:7], v[6:7], v[46:47]
	v_and_b32_e32 v49, 0xffff0000, v16
	v_pk_add_f32 v[4:5], v[4:5], v[10:11]
	s_waitcnt vmcnt(3)
	v_lshlrev_b32_e32 v10, 16, v18
	v_and_b32_e32 v11, 0xffff0000, v18
	v_lshlrev_b32_e32 v12, 16, v19
	v_and_b32_e32 v13, 0xffff0000, v19
	v_pk_add_f32 v[8:9], v[8:9], v[48:49]
	v_pk_add_f32 v[6:7], v[6:7], v[10:11]
	v_pk_add_f32 v[2:3], v[2:3], v[12:13]
	v_lshlrev_b32_e32 v10, 16, v20
	v_and_b32_e32 v11, 0xffff0000, v20
	v_lshlrev_b32_e32 v12, 16, v21
	v_and_b32_e32 v13, 0xffff0000, v21
	v_pk_add_f32 v[8:9], v[8:9], v[10:11]
	v_pk_add_f32 v[4:5], v[4:5], v[12:13]
	s_waitcnt vmcnt(2)
	v_lshlrev_b32_e32 v10, 16, v22
	v_and_b32_e32 v11, 0xffff0000, v22
	v_lshlrev_b32_e32 v12, 16, v23
	v_and_b32_e32 v13, 0xffff0000, v23
	v_pk_add_f32 v[2:3], v[2:3], v[12:13]
	v_pk_add_f32 v[6:7], v[6:7], v[10:11]
	v_lshlrev_b32_e32 v10, 16, v24
	v_and_b32_e32 v11, 0xffff0000, v24
	v_lshlrev_b32_e32 v12, 16, v25
	v_and_b32_e32 v13, 0xffff0000, v25
	v_pk_add_f32 v[4:5], v[4:5], v[12:13]
	v_pk_add_f32 v[8:9], v[8:9], v[10:11]
	s_waitcnt vmcnt(1)
	v_lshlrev_b32_e32 v10, 16, v26
	v_and_b32_e32 v11, 0xffff0000, v26
	v_lshlrev_b32_e32 v12, 16, v27
	v_and_b32_e32 v13, 0xffff0000, v27
	v_pk_add_f32 v[6:7], v[6:7], v[10:11]
	v_pk_add_f32 v[2:3], v[2:3], v[12:13]
	v_lshlrev_b32_e32 v10, 16, v28
	v_and_b32_e32 v11, 0xffff0000, v28
	v_lshlrev_b32_e32 v12, 16, v29
	v_and_b32_e32 v13, 0xffff0000, v29
	v_pk_add_f32 v[8:9], v[8:9], v[10:11]
	v_pk_add_f32 v[4:5], v[4:5], v[12:13]
	s_waitcnt vmcnt(0)
	v_lshlrev_b32_e32 v10, 16, v30
	v_and_b32_e32 v11, 0xffff0000, v30
	v_lshlrev_b32_e32 v12, 16, v31
	v_and_b32_e32 v13, 0xffff0000, v31
	v_pk_add_f32 v[72:73], v[2:3], v[12:13]
	v_pk_add_f32 v[70:71], v[6:7], v[10:11]
	v_lshlrev_b32_e32 v2, 16, v32
	v_and_b32_e32 v3, 0xffff0000, v32
	v_lshlrev_b32_e32 v6, 16, v33
	v_and_b32_e32 v7, 0xffff0000, v33
	v_pk_add_f32 v[68:69], v[4:5], v[6:7]
	v_pk_add_f32 v[66:67], v[8:9], v[2:3]

	.amdhsa_kernel _Z9hymba_fwd4Args
		.amdhsa_group_segment_fixed_size 0
		.amdhsa_private_segment_fixed_size 0
		.amdhsa_kernarg_size 408
		.amdhsa_user_sgpr_count 2
		.amdhsa_user_sgpr_dispatch_ptr 0
		.amdhsa_user_sgpr_queue_ptr 0
		.amdhsa_user_sgpr_kernarg_segment_ptr 1
		.amdhsa_user_sgpr_dispatch_id 0
		.amdhsa_user_sgpr_kernarg_preload_length 0
		.amdhsa_user_sgpr_kernarg_preload_offset 0
		.amdhsa_user_sgpr_private_segment_size 0
		.amdhsa_uses_dynamic_stack 0
		.amdhsa_enable_private_segment 0
		.amdhsa_system_sgpr_workgroup_id_x 1
		.amdhsa_system_sgpr_workgroup_id_y 0
		.amdhsa_system_sgpr_workgroup_id_z 0
		.amdhsa_system_sgpr_workgroup_info 0
		.amdhsa_system_vgpr_workitem_id 0
		.amdhsa_next_free_vgpr 256
		.amdhsa_next_free_sgpr 102
		.amdhsa_accum_offset 256
		.amdhsa_reserve_vcc 1
		.amdhsa_float_round_mode_32 0
		.amdhsa_float_round_mode_16_64 0
		.amdhsa_float_denorm_mode_32 3
		.amdhsa_float_denorm_mode_16_64 3
		.amdhsa_dx10_clamp 1
		.amdhsa_ieee_mode 1
		.amdhsa_fp16_overflow 0
		.amdhsa_tg_split 0
		.amdhsa_exception_fp_ieee_invalid_op 0
		.amdhsa_exception_fp_denorm_src 0
		.amdhsa_exception_fp_ieee_div_zero 0
		.amdhsa_exception_fp_ieee_overflow 0
		.amdhsa_exception_fp_ieee_underflow 0
		.amdhsa_exception_fp_ieee_inexact 0
		.amdhsa_exception_int_div_zero 0
	.end_amdhsa_kernel

amdhsa.kernels:
  - .agpr_count:     0
    .args:
      - .offset:         0
        .size:           152
        .value_kind:     by_value
      - .offset:         152
        .size:           4
        .value_kind:     hidden_block_count_x
      - .offset:         156
        .size:           4
        .value_kind:     hidden_block_count_y
      - .offset:         160
        .size:           4
        .value_kind:     hidden_block_count_z
      - .offset:         164
        .size:           2
        .value_kind:     hidden_group_size_x
      - .offset:         166
        .size:           2
        .value_kind:     hidden_group_size_y
      - .offset:         168
        .size:           2
        .value_kind:     hidden_group_size_z
      - .offset:         170
        .size:           2
        .value_kind:     hidden_remainder_x
      - .offset:         172
        .size:           2
        .value_kind:     hidden_remainder_y
      - .offset:         174
        .size:           2
        .value_kind:     hidden_remainder_z
      - .offset:         192
        .size:           8
        .value_kind:     hidden_global_offset_x
      - .offset:         200
        .size:           8
        .value_kind:     hidden_global_offset_y
      - .offset:         208
        .size:           8
        .value_kind:     hidden_global_offset_z
      - .offset:         216
        .size:           2
        .value_kind:     hidden_grid_dims
      - .offset:         272
        .size:           4
        .value_kind:     hidden_dynamic_lds_size
    .group_segment_fixed_size: 0
    .kernarg_segment_align: 8
    .kernarg_segment_size: 408
    .language:       OpenCL C
    .language_version:
      - 2
      - 0
    .max_flat_workgroup_size: 512
    .name:           _Z9hymba_fwd4Args
    .private_segment_fixed_size: 0
    .sgpr_count:     108
    .sgpr_spill_count: 135
    .symbol:         _Z9hymba_fwd4Args.kd
    .uniform_work_group_size: 1
    .uses_dynamic_stack: false
    .vgpr_count:     256
    .vgpr_spill_count: 0
    .wavefront_size: 64
